# inproj u stores write-through (sc1): no dirty lines left in L2 for the phase-end writeback, no L2 pollution by the 243 MB/layer activation stream
# speedup vs baseline: 1.0137x; 1.0137x over previous
; template <class LA, class LB, class EP>
; __device__ __forceinline__ void gemm_tile_big(int K, LA loadA, LB loadB, EP epi, char* smem) {
;     ...
;   for (int kt = 0; kt < nk; ++kt) {
;     __syncthreads();
; #pragma unroll
;     for (int i = 0; i < 8; ++i) *(uint4*)&sA[(lr + 32 * i) * 72 + lc] = ra[i];
; #pragma unroll
;     for (int i = 0; i < 4; ++i) *(uint4*)&sB[(lr + 32 * i) * 72 + lc] = rb[i];
;     __syncthreads();
;     if (kt + 1 < nk) {
;       const int kk = (kt + 1) * 64 + lc;
; #pragma unroll
;       for (int i = 0; i < 8; ++i) ra[i] = loadA(lr + 32 * i, kk);
; #pragma unroll
;       for (int i = 0; i < 4; ++i) rb[i] = loadB(lr + 32 * i, kk);
;     }
; #pragma unroll
;     for (int s = 0; s < 4; ++s) {
;       h8 af[4], bf[2];
; #pragma unroll
;       for (int mi = 0; mi < 4; ++mi)
;         af[mi] = *(const h8*)&sA[(wm * 128 + mi * 32 + (lane & 31)) * 72 + s * 16 + (lane >> 5) * 8];
; #pragma unroll
;       for (int ni = 0; ni < 2; ++ni)
;         bf[ni] = *(const h8*)&sB[(wn * 64 + ni * 32 + (lane & 31)) * 72 + s * 16 + (lane >> 5) * 8];
; #pragma unroll
;       for (int mi = 0; mi < 4; ++mi)
; #pragma unroll
;         for (int ni = 0; ni < 2; ++ni)
;           acc[mi][ni] = __builtin_amdgcn_mfma_f32_32x32x16_f16(af[mi], bf[ni], acc[mi][ni], 0, 0, 0);
;     }
.Lgp1_loop:
	ds_read_b128 v[238:241], v179 offset:20480
	ds_read_b128 v[242:245], v179 offset:23040
	ds_read_b128 v[200:203], v178
	ds_read_b128 v[204:207], v178 offset:2560
	ds_read_b128 v[214:217], v178 offset:5120
	ds_read_b128 v[218:221], v178 offset:7680
	global_load_dwordx4 v[130:133], v208, s[38:39] sc1
	global_load_dwordx4 v[134:137], v209, s[38:39] sc1
	global_load_dwordx4 v[138:141], v210, s[38:39] sc1
	global_load_dwordx4 v[142:145], v211, s[38:39] sc1
	global_load_dwordx4 v[146:149], v208, s[2:3] sc1
	global_load_dwordx4 v[150:153], v209, s[2:3] sc1
	s_add_u32 s38, s38, 0x100000
	s_addc_u32 s39, s39, 0
	s_add_u32 s2, s2, 0x74000
	s_addc_u32 s3, s3, 0
	ds_read_b128 v[226:229], v179 offset:20512
	ds_read_b128 v[230:233], v179 offset:23072
	s_waitcnt lgkmcnt(5)
	v_mfma_f32_32x32x16_f16 v[114:129], v[200:203], v[238:241], v[114:129]
	v_mfma_f32_32x32x16_f16 v[98:113], v[200:203], v[242:245], v[98:113]
	ds_read_b128 v[200:203], v178 offset:32
	s_waitcnt lgkmcnt(5)
	v_mfma_f32_32x32x16_f16 v[82:97], v[204:207], v[238:241], v[82:97]
	v_mfma_f32_32x32x16_f16 v[66:81], v[204:207], v[242:245], v[66:81]
	ds_read_b128 v[204:207], v178 offset:2592
	s_waitcnt vmcnt(11)
	ds_write_b128 v196, v[154:157] offset:30720
	s_waitcnt lgkmcnt(6)
	v_mfma_f32_32x32x16_f16 v[50:65], v[214:217], v[238:241], v[50:65]
	v_mfma_f32_32x32x16_f16 v[34:49], v[214:217], v[242:245], v[34:49]
	ds_read_b128 v[214:217], v178 offset:5152
	s_waitcnt vmcnt(10)
	ds_write_b128 v196, v[158:161] offset:35840
	s_waitcnt lgkmcnt(7)
	v_mfma_f32_32x32x16_f16 v[18:33], v[218:221], v[238:241], v[18:33]
	v_mfma_f32_32x32x16_f16 v[2:17], v[218:221], v[242:245], v[2:17]
	ds_read_b128 v[218:221], v178 offset:7712
	s_waitcnt vmcnt(9)
	ds_write_b128 v196, v[162:165] offset:40960
	s_waitcnt lgkmcnt(6)
	v_mfma_f32_32x32x16_f16 v[114:129], v[200:203], v[226:229], v[114:129]
	v_mfma_f32_32x32x16_f16 v[98:113], v[200:203], v[230:233], v[98:113]
	s_waitcnt vmcnt(8)
	ds_write_b128 v196, v[166:169] offset:46080
	s_waitcnt lgkmcnt(6)
	v_mfma_f32_32x32x16_f16 v[82:97], v[204:207], v[226:229], v[82:97]
	v_mfma_f32_32x32x16_f16 v[66:81], v[204:207], v[230:233], v[66:81]
	s_waitcnt vmcnt(7)
	ds_write_b128 v196, v[170:173] offset:51200
	s_waitcnt lgkmcnt(5)
	v_mfma_f32_32x32x16_f16 v[50:65], v[214:217], v[226:229], v[50:65]
	v_mfma_f32_32x32x16_f16 v[34:49], v[214:217], v[230:233], v[34:49]
	s_waitcnt vmcnt(6)
	ds_write_b128 v196, v[174:177] offset:56320
	s_waitcnt lgkmcnt(4)
	v_mfma_f32_32x32x16_f16 v[18:33], v[218:221], v[226:229], v[18:33]
	v_mfma_f32_32x32x16_f16 v[2:17], v[218:221], v[230:233], v[2:17]
	s_waitcnt lgkmcnt(0)
	s_barrier
	ds_read_b128 v[238:241], v179 offset:51200
	ds_read_b128 v[242:245], v179 offset:53760
	ds_read_b128 v[200:203], v178 offset:30720
	ds_read_b128 v[204:207], v178 offset:33280
	ds_read_b128 v[214:217], v178 offset:35840
	ds_read_b128 v[218:221], v178 offset:38400
	global_load_dwordx4 v[154:157], v208, s[38:39] sc1
	global_load_dwordx4 v[158:161], v209, s[38:39] sc1
	global_load_dwordx4 v[162:165], v210, s[38:39] sc1
	global_load_dwordx4 v[166:169], v211, s[38:39] sc1
	global_load_dwordx4 v[170:173], v208, s[2:3] sc1
	global_load_dwordx4 v[174:177], v209, s[2:3] sc1
	s_add_u32 s38, s38, 0x100000
	s_addc_u32 s39, s39, 0
	s_add_u32 s2, s2, 0x74000
	s_addc_u32 s3, s3, 0
	ds_read_b128 v[226:229], v179 offset:51232
	ds_read_b128 v[230:233], v179 offset:53792
	s_waitcnt lgkmcnt(5)
	v_mfma_f32_32x32x16_f16 v[114:129], v[200:203], v[238:241], v[114:129]
	v_mfma_f32_32x32x16_f16 v[98:113], v[200:203], v[242:245], v[98:113]
	ds_read_b128 v[200:203], v178 offset:30752
	s_waitcnt lgkmcnt(5)
	v_mfma_f32_32x32x16_f16 v[82:97], v[204:207], v[238:241], v[82:97]
	v_mfma_f32_32x32x16_f16 v[66:81], v[204:207], v[242:245], v[66:81]
	ds_read_b128 v[204:207], v178 offset:33312
	s_waitcnt vmcnt(11)
	ds_write_b128 v196, v[130:133]
	s_waitcnt lgkmcnt(6)
	v_mfma_f32_32x32x16_f16 v[50:65], v[214:217], v[238:241], v[50:65]
	v_mfma_f32_32x32x16_f16 v[34:49], v[214:217], v[242:245], v[34:49]
	ds_read_b128 v[214:217], v178 offset:35872
	s_waitcnt vmcnt(10)
	ds_write_b128 v196, v[134:137] offset:5120
	s_waitcnt lgkmcnt(7)
	v_mfma_f32_32x32x16_f16 v[18:33], v[218:221], v[238:241], v[18:33]
	v_mfma_f32_32x32x16_f16 v[2:17], v[218:221], v[242:245], v[2:17]
	ds_read_b128 v[218:221], v178 offset:38432
	s_waitcnt vmcnt(9)
	ds_write_b128 v196, v[138:141] offset:10240
	s_waitcnt lgkmcnt(6)
	v_mfma_f32_32x32x16_f16 v[114:129], v[200:203], v[226:229], v[114:129]
	v_mfma_f32_32x32x16_f16 v[98:113], v[200:203], v[230:233], v[98:113]
	s_waitcnt vmcnt(8)
	ds_write_b128 v196, v[142:145] offset:15360
	s_waitcnt lgkmcnt(6)
	v_mfma_f32_32x32x16_f16 v[82:97], v[204:207], v[226:229], v[82:97]
	v_mfma_f32_32x32x16_f16 v[66:81], v[204:207], v[230:233], v[66:81]
	s_waitcnt vmcnt(7)
	ds_write_b128 v196, v[146:149] offset:20480
	s_waitcnt lgkmcnt(5)
	v_mfma_f32_32x32x16_f16 v[50:65], v[214:217], v[226:229], v[50:65]
	v_mfma_f32_32x32x16_f16 v[34:49], v[214:217], v[230:233], v[34:49]
	s_waitcnt vmcnt(6)
	ds_write_b128 v196, v[150:153] offset:25600
	s_waitcnt lgkmcnt(4)
	v_mfma_f32_32x32x16_f16 v[18:33], v[218:221], v[226:229], v[18:33]
	v_mfma_f32_32x32x16_f16 v[2:17], v[218:221], v[230:233], v[2:17]
	s_waitcnt lgkmcnt(0)
	s_barrier
	s_add_i32 s30, s30, 1
	s_cmp_lt_u32 s30, 15
	s_cbranch_scc1 .Lgp1_loop
;   __device__ __forceinline__ half_t* u() const { return (half_t*)(ws() + OFF_u); }
; template <class LA, class LB, class EP>
; __device__ __forceinline__ void gemm_tile_big(int K, LA loadA, LB loadB, EP epi, char* smem) {
;     ...
;     if (kt + 1 < nk) {
;       const int kk = (kt + 1) * 64 + lc;
; #pragma unroll
;       for (int i = 0; i < 8; ++i) ra[i] = loadA(lr + 32 * i, kk);
; #pragma unroll
;       for (int i = 0; i < 4; ++i) rb[i] = loadB(lr + 32 * i, kk);
;     }
; #pragma unroll
;     for (int s = 0; s < 4; ++s) {
;       h8 af[4], bf[2];
; #pragma unroll
;       for (int mi = 0; mi < 4; ++mi)
;         af[mi] = *(const h8*)&sA[(wm * 128 + mi * 32 + (lane & 31)) * 72 + s * 16 + (lane >> 5) * 8];
; #pragma unroll
;       for (int ni = 0; ni < 2; ++ni)
;         bf[ni] = *(const h8*)&sB[(wn * 64 + ni * 32 + (lane & 31)) * 72 + s * 16 + (lane >> 5) * 8];
; #pragma unroll
;       for (int mi = 0; mi < 4; ++mi)
; #pragma unroll
;         for (int ni = 0; ni < 2; ++ni)
;           acc[mi][ni] = __builtin_amdgcn_mfma_f32_32x32x16_f16(af[mi], bf[ni], acc[mi][ni], 0, 0, 0);
;     }
; __device__ __forceinline__ void phase_inproj(const KP& p, int l, char* smem, int* q, int xcc) {
;     ...
;         [&](int mi, int ni, int r, int row, int col, float v) {
;           const half_t hv = (half_t)(v + bv[ni]);
;           const int tok = m0 + row;
;           p.u()[(size_t)tok * NU + n0 + col] = hv;
	ds_read_b128 v[238:241], v179 offset:20480
	ds_read_b128 v[242:245], v179 offset:23040
	ds_read_b128 v[200:203], v178
	ds_read_b128 v[204:207], v178 offset:2560
	ds_read_b128 v[214:217], v178 offset:5120
	ds_read_b128 v[218:221], v178 offset:7680
	ds_read_b128 v[226:229], v179 offset:20512
	ds_read_b128 v[230:233], v179 offset:23072
	s_waitcnt lgkmcnt(5)
	v_mfma_f32_32x32x16_f16 v[114:129], v[200:203], v[238:241], v[114:129]
	v_mfma_f32_32x32x16_f16 v[98:113], v[200:203], v[242:245], v[98:113]
	ds_read_b128 v[200:203], v178 offset:32
	s_waitcnt lgkmcnt(5)
	v_mfma_f32_32x32x16_f16 v[82:97], v[204:207], v[238:241], v[82:97]
	v_mfma_f32_32x32x16_f16 v[66:81], v[204:207], v[242:245], v[66:81]
	ds_read_b128 v[204:207], v178 offset:2592
	s_waitcnt vmcnt(5)
	ds_write_b128 v196, v[154:157] offset:30720
	s_waitcnt lgkmcnt(6)
	v_mfma_f32_32x32x16_f16 v[50:65], v[214:217], v[238:241], v[50:65]
	v_mfma_f32_32x32x16_f16 v[34:49], v[214:217], v[242:245], v[34:49]
	ds_read_b128 v[214:217], v178 offset:5152
	s_waitcnt vmcnt(4)
	ds_write_b128 v196, v[158:161] offset:35840
	s_waitcnt lgkmcnt(7)
	v_mfma_f32_32x32x16_f16 v[18:33], v[218:221], v[238:241], v[18:33]
	v_mfma_f32_32x32x16_f16 v[2:17], v[218:221], v[242:245], v[2:17]
	ds_read_b128 v[218:221], v178 offset:7712
	s_waitcnt vmcnt(3)
	ds_write_b128 v196, v[162:165] offset:40960
	s_waitcnt lgkmcnt(6)
	v_mfma_f32_32x32x16_f16 v[114:129], v[200:203], v[226:229], v[114:129]
	v_mfma_f32_32x32x16_f16 v[98:113], v[200:203], v[230:233], v[98:113]
	s_waitcnt vmcnt(2)
	ds_write_b128 v196, v[166:169] offset:46080
	s_waitcnt lgkmcnt(6)
	v_mfma_f32_32x32x16_f16 v[82:97], v[204:207], v[226:229], v[82:97]
	v_mfma_f32_32x32x16_f16 v[66:81], v[204:207], v[230:233], v[66:81]
	s_waitcnt vmcnt(1)
	ds_write_b128 v196, v[170:173] offset:51200
	s_waitcnt lgkmcnt(5)
	v_mfma_f32_32x32x16_f16 v[50:65], v[214:217], v[226:229], v[50:65]
	v_mfma_f32_32x32x16_f16 v[34:49], v[214:217], v[230:233], v[34:49]
	s_waitcnt vmcnt(0)
	ds_write_b128 v196, v[174:177] offset:56320
	s_waitcnt lgkmcnt(4)
	v_mfma_f32_32x32x16_f16 v[18:33], v[218:221], v[226:229], v[18:33]
	v_mfma_f32_32x32x16_f16 v[2:17], v[218:221], v[230:233], v[2:17]
	s_waitcnt lgkmcnt(0)
	s_barrier
	ds_read_b128 v[238:241], v179 offset:51200
	ds_read_b128 v[242:245], v179 offset:53760
	ds_read_b128 v[200:203], v178 offset:30720
	ds_read_b128 v[204:207], v178 offset:33280
	ds_read_b128 v[214:217], v178 offset:35840
	ds_read_b128 v[218:221], v178 offset:38400
	ds_read_b128 v[226:229], v179 offset:51232
	ds_read_b128 v[230:233], v179 offset:53792
	s_waitcnt lgkmcnt(5)
	v_mfma_f32_32x32x16_f16 v[114:129], v[200:203], v[238:241], v[114:129]
	v_mfma_f32_32x32x16_f16 v[98:113], v[200:203], v[242:245], v[98:113]
	ds_read_b128 v[200:203], v178 offset:30752
	s_waitcnt lgkmcnt(5)
	v_mfma_f32_32x32x16_f16 v[82:97], v[204:207], v[238:241], v[82:97]
	v_mfma_f32_32x32x16_f16 v[66:81], v[204:207], v[242:245], v[66:81]
	ds_read_b128 v[204:207], v178 offset:33312
	s_waitcnt lgkmcnt(5)
	v_mfma_f32_32x32x16_f16 v[50:65], v[214:217], v[238:241], v[50:65]
	v_mfma_f32_32x32x16_f16 v[34:49], v[214:217], v[242:245], v[34:49]
	ds_read_b128 v[214:217], v178 offset:35872
	s_waitcnt lgkmcnt(5)
	v_mfma_f32_32x32x16_f16 v[18:33], v[218:221], v[238:241], v[18:33]
	v_mfma_f32_32x32x16_f16 v[2:17], v[218:221], v[242:245], v[2:17]
	ds_read_b128 v[218:221], v178 offset:38432
	s_waitcnt lgkmcnt(3)
	v_mfma_f32_32x32x16_f16 v[114:129], v[200:203], v[226:229], v[114:129]
	v_mfma_f32_32x32x16_f16 v[98:113], v[200:203], v[230:233], v[98:113]
	s_waitcnt lgkmcnt(2)
	v_mfma_f32_32x32x16_f16 v[82:97], v[204:207], v[226:229], v[82:97]
	v_mfma_f32_32x32x16_f16 v[66:81], v[204:207], v[230:233], v[66:81]
	s_waitcnt lgkmcnt(1)
	v_mfma_f32_32x32x16_f16 v[50:65], v[214:217], v[226:229], v[50:65]
	v_mfma_f32_32x32x16_f16 v[34:49], v[214:217], v[230:233], v[34:49]
	s_waitcnt lgkmcnt(0)
	v_mfma_f32_32x32x16_f16 v[18:33], v[218:221], v[226:229], v[18:33]
	v_mfma_f32_32x32x16_f16 v[2:17], v[218:221], v[230:233], v[2:17]
	s_waitcnt lgkmcnt(0)
	v_mov_b32_e32 v226, 1
	v_mov_b32_e32 v227, 0x11fe0
	v_mov_b32_e32 v228, 0x11fe4
	v_mov_b32_e32 v229, 0x100
	v_mov_b32_e32 v230, 2
	v_mov_b32_e32 v231, 0x3727c5ac
	v_mov_b32_e32 v232, 0x11fa0
	v_mov_b32_e32 v233, 0x80000
	v_mov_b32_e32 v238, 0x4000
	v_mov_b32_e32 v239, 0x4400
	v_mov_b32_e32 v240, 0x4800
	v_mov_b32_e32 v241, 0x4c00
	v_mov_b32_e32 v242, 0xf149f2ca
	v_mov_b32_e32 v243, 0x200
	v_mov_b32_e32 v244, 0x400
	v_mov_b32_e32 v245, 0x600
	s_nop 15
	s_lshl_b32 s14, s14, 8
	s_lshl_b64 s[2:3], s[18:19], 1
	s_add_u32 s18, s47, s2
	s_addc_u32 s19, s48, s3
	s_mul_i32 s2, s14, 0x3a00
	s_add_u32 s18, s18, s2
	s_addc_u32 s19, s19, 0
	v_lshrrev_b32_e32 v130, 7, v224
	v_lshlrev_b32_e32 v130, 5, v130
	v_bfe_u32 v131, v224, 5, 1
	v_add_u32_e32 v130, v130, v131
	v_mul_u32_u24_e32 v132, 0xe800, v130
	v_bfe_u32 v131, v224, 6, 1
	v_and_b32_e32 v133, 31, v224
	v_lshl_or_b32 v134, v131, 6, v133
	v_lshl_add_u32 v132, v134, 1, v132
	v_add_f32_e32 v114, v246, v114
	v_cvt_f16_f32_e32 v114, v114
	v_add_f32_e32 v115, v246, v115
	v_cvt_f16_f32_e32 v115, v115
	v_add_f32_e32 v116, v246, v116
	v_cvt_f16_f32_e32 v116, v116
	v_add_f32_e32 v117, v246, v117
	v_cvt_f16_f32_e32 v117, v117
	v_add_f32_e32 v118, v246, v118
	v_cvt_f16_f32_e32 v118, v118
	v_add_f32_e32 v119, v246, v119
	v_cvt_f16_f32_e32 v119, v119
	v_add_f32_e32 v120, v246, v120
	v_cvt_f16_f32_e32 v120, v120
	v_add_f32_e32 v121, v246, v121
	v_cvt_f16_f32_e32 v121, v121
	v_add_f32_e32 v122, v246, v122
	v_cvt_f16_f32_e32 v122, v122
	v_add_f32_e32 v123, v246, v123
	v_cvt_f16_f32_e32 v123, v123
	v_add_f32_e32 v124, v246, v124
	v_cvt_f16_f32_e32 v124, v124
; __device__ __forceinline__ void phase_inproj(const KP& p, int l, char* smem, int* q, int xcc) {
;     ...
;         [&](int mi, int ni, int r, int row, int col, float v) {
;           const half_t hv = (half_t)(v + bv[ni]);
	v_add_f32_e32 v125, v246, v125
	v_cvt_f16_f32_e32 v125, v125
	v_add_f32_e32 v126, v246, v126
	v_cvt_f16_f32_e32 v126, v126
	v_add_f32_e32 v127, v246, v127
	v_cvt_f16_f32_e32 v127, v127
	v_add_f32_e32 v128, v246, v128
	v_cvt_f16_f32_e32 v128, v128
	v_add_f32_e32 v129, v246, v129
	v_cvt_f16_f32_e32 v129, v129
	v_add_f32_e32 v98, v187, v98
	v_cvt_f16_f32_e32 v98, v98
	v_add_f32_e32 v99, v187, v99
	v_cvt_f16_f32_e32 v99, v99
	v_add_f32_e32 v100, v187, v100
	v_cvt_f16_f32_e32 v100, v100
	v_add_f32_e32 v101, v187, v101
	v_cvt_f16_f32_e32 v101, v101
	v_add_f32_e32 v102, v187, v102
	v_cvt_f16_f32_e32 v102, v102
	v_add_f32_e32 v103, v187, v103
	v_cvt_f16_f32_e32 v103, v103
	v_add_f32_e32 v104, v187, v104
	v_cvt_f16_f32_e32 v104, v104
	v_add_f32_e32 v105, v187, v105
	v_cvt_f16_f32_e32 v105, v105
	v_add_f32_e32 v106, v187, v106
	v_cvt_f16_f32_e32 v106, v106
	v_add_f32_e32 v107, v187, v107
	v_cvt_f16_f32_e32 v107, v107
	v_add_f32_e32 v108, v187, v108
	v_cvt_f16_f32_e32 v108, v108
	v_add_f32_e32 v109, v187, v109
	v_cvt_f16_f32_e32 v109, v109
	v_add_f32_e32 v110, v187, v110
	v_cvt_f16_f32_e32 v110, v110
	v_add_f32_e32 v111, v187, v111
	v_cvt_f16_f32_e32 v111, v111
	v_add_f32_e32 v112, v187, v112
	v_cvt_f16_f32_e32 v112, v112
	v_add_f32_e32 v113, v187, v113
	v_cvt_f16_f32_e32 v113, v113
	v_add_f32_e32 v82, v246, v82
	v_cvt_f16_f32_e32 v82, v82
	v_add_f32_e32 v83, v246, v83
	v_cvt_f16_f32_e32 v83, v83
	v_add_f32_e32 v84, v246, v84
	v_cvt_f16_f32_e32 v84, v84
	v_add_f32_e32 v85, v246, v85
	v_cvt_f16_f32_e32 v85, v85
	v_add_f32_e32 v86, v246, v86
	v_cvt_f16_f32_e32 v86, v86
	v_add_f32_e32 v87, v246, v87
	v_cvt_f16_f32_e32 v87, v87
	v_add_f32_e32 v88, v246, v88
	v_cvt_f16_f32_e32 v88, v88
	v_add_f32_e32 v89, v246, v89
	v_cvt_f16_f32_e32 v89, v89
	v_add_f32_e32 v90, v246, v90
	v_cvt_f16_f32_e32 v90, v90
	v_add_f32_e32 v91, v246, v91
	v_cvt_f16_f32_e32 v91, v91
	v_add_f32_e32 v92, v246, v92
	v_cvt_f16_f32_e32 v92, v92
	v_add_f32_e32 v93, v246, v93
	v_cvt_f16_f32_e32 v93, v93
	v_add_f32_e32 v94, v246, v94
	v_cvt_f16_f32_e32 v94, v94
	v_add_f32_e32 v95, v246, v95
	v_cvt_f16_f32_e32 v95, v95
	v_add_f32_e32 v96, v246, v96
	v_cvt_f16_f32_e32 v96, v96
	v_add_f32_e32 v97, v246, v97
	v_cvt_f16_f32_e32 v97, v97
	v_add_f32_e32 v66, v187, v66
	v_cvt_f16_f32_e32 v66, v66
	v_add_f32_e32 v67, v187, v67
	v_cvt_f16_f32_e32 v67, v67
	v_add_f32_e32 v68, v187, v68
	v_cvt_f16_f32_e32 v68, v68
	v_add_f32_e32 v69, v187, v69
	v_cvt_f16_f32_e32 v69, v69
	v_add_f32_e32 v70, v187, v70
	v_cvt_f16_f32_e32 v70, v70
	v_add_f32_e32 v71, v187, v71
	v_cvt_f16_f32_e32 v71, v71
	v_add_f32_e32 v72, v187, v72
	v_cvt_f16_f32_e32 v72, v72
	v_add_f32_e32 v73, v187, v73
	v_cvt_f16_f32_e32 v73, v73
	v_add_f32_e32 v74, v187, v74
	v_cvt_f16_f32_e32 v74, v74
	v_add_f32_e32 v75, v187, v75
	v_cvt_f16_f32_e32 v75, v75
	v_add_f32_e32 v76, v187, v76
	v_cvt_f16_f32_e32 v76, v76
	v_add_f32_e32 v77, v187, v77
	v_cvt_f16_f32_e32 v77, v77
	v_add_f32_e32 v78, v187, v78
	v_cvt_f16_f32_e32 v78, v78
	v_add_f32_e32 v79, v187, v79
	v_cvt_f16_f32_e32 v79, v79
	v_add_f32_e32 v80, v187, v80
	v_cvt_f16_f32_e32 v80, v80
	v_add_f32_e32 v81, v187, v81
	v_cvt_f16_f32_e32 v81, v81
	v_add_f32_e32 v50, v246, v50
	v_cvt_f16_f32_e32 v50, v50
	v_add_f32_e32 v51, v246, v51
	v_cvt_f16_f32_e32 v51, v51
	v_add_f32_e32 v52, v246, v52
	v_cvt_f16_f32_e32 v52, v52
	v_add_f32_e32 v53, v246, v53
	v_cvt_f16_f32_e32 v53, v53
	v_add_f32_e32 v54, v246, v54
	v_cvt_f16_f32_e32 v54, v54
	v_add_f32_e32 v55, v246, v55
	v_cvt_f16_f32_e32 v55, v55
	v_add_f32_e32 v56, v246, v56
	v_cvt_f16_f32_e32 v56, v56
	v_add_f32_e32 v57, v246, v57
	v_cvt_f16_f32_e32 v57, v57
	v_add_f32_e32 v58, v246, v58
	v_cvt_f16_f32_e32 v58, v58
	v_add_f32_e32 v59, v246, v59
	v_cvt_f16_f32_e32 v59, v59
	v_add_f32_e32 v60, v246, v60
	v_cvt_f16_f32_e32 v60, v60
	v_add_f32_e32 v61, v246, v61
	v_cvt_f16_f32_e32 v61, v61
	v_add_f32_e32 v62, v246, v62
	v_cvt_f16_f32_e32 v62, v62
	v_add_f32_e32 v63, v246, v63
	v_cvt_f16_f32_e32 v63, v63
	v_add_f32_e32 v64, v246, v64
	v_cvt_f16_f32_e32 v64, v64
	v_add_f32_e32 v65, v246, v65
	v_cvt_f16_f32_e32 v65, v65
	v_add_f32_e32 v34, v187, v34
	v_cvt_f16_f32_e32 v34, v34
	v_add_f32_e32 v35, v187, v35
	v_cvt_f16_f32_e32 v35, v35
	v_add_f32_e32 v36, v187, v36
	v_cvt_f16_f32_e32 v36, v36
	v_add_f32_e32 v37, v187, v37
	v_cvt_f16_f32_e32 v37, v37
	v_add_f32_e32 v38, v187, v38
	v_cvt_f16_f32_e32 v38, v38
	v_add_f32_e32 v39, v187, v39
	v_cvt_f16_f32_e32 v39, v39
	v_add_f32_e32 v40, v187, v40
	v_cvt_f16_f32_e32 v40, v40
	v_add_f32_e32 v41, v187, v41
	v_cvt_f16_f32_e32 v41, v41
	v_add_f32_e32 v42, v187, v42
	v_cvt_f16_f32_e32 v42, v42
	v_add_f32_e32 v43, v187, v43
	v_cvt_f16_f32_e32 v43, v43
	v_add_f32_e32 v44, v187, v44
	v_cvt_f16_f32_e32 v44, v44
	v_add_f32_e32 v45, v187, v45
	v_cvt_f16_f32_e32 v45, v45
	v_add_f32_e32 v46, v187, v46
	v_cvt_f16_f32_e32 v46, v46
	v_add_f32_e32 v47, v187, v47
	v_cvt_f16_f32_e32 v47, v47
	v_add_f32_e32 v48, v187, v48
	v_cvt_f16_f32_e32 v48, v48
	v_add_f32_e32 v49, v187, v49
	v_cvt_f16_f32_e32 v49, v49
	v_add_f32_e32 v18, v246, v18
	v_cvt_f16_f32_e32 v18, v18
	v_add_f32_e32 v19, v246, v19
	v_cvt_f16_f32_e32 v19, v19
	v_add_f32_e32 v20, v246, v20
	v_cvt_f16_f32_e32 v20, v20
	v_add_f32_e32 v21, v246, v21
	v_cvt_f16_f32_e32 v21, v21
	v_add_f32_e32 v22, v246, v22
	v_cvt_f16_f32_e32 v22, v22
	v_add_f32_e32 v23, v246, v23
	v_cvt_f16_f32_e32 v23, v23
	v_add_f32_e32 v24, v246, v24
	v_cvt_f16_f32_e32 v24, v24
	v_add_f32_e32 v25, v246, v25
	v_cvt_f16_f32_e32 v25, v25
	v_add_f32_e32 v26, v246, v26
	v_cvt_f16_f32_e32 v26, v26
	v_add_f32_e32 v27, v246, v27
	v_cvt_f16_f32_e32 v27, v27
	v_add_f32_e32 v28, v246, v28
	v_cvt_f16_f32_e32 v28, v28
;   __device__ __forceinline__ half_t* u() const { return (half_t*)(ws() + OFF_u); }
; __device__ __forceinline__ void phase_inproj(const KP& p, int l, char* smem, int* q, int xcc) {
;     ...
;           const half_t hv = (half_t)(v + bv[ni]);
;           const int tok = m0 + row;
;           p.u()[(size_t)tok * NU + n0 + col] = hv;
	v_add_f32_e32 v29, v246, v29
	v_cvt_f16_f32_e32 v29, v29
	v_add_f32_e32 v30, v246, v30
	v_cvt_f16_f32_e32 v30, v30
	v_add_f32_e32 v31, v246, v31
	v_cvt_f16_f32_e32 v31, v31
	v_add_f32_e32 v32, v246, v32
	v_cvt_f16_f32_e32 v32, v32
	v_add_f32_e32 v33, v246, v33
	v_cvt_f16_f32_e32 v33, v33
	v_add_f32_e32 v2, v187, v2
	v_cvt_f16_f32_e32 v2, v2
	v_add_f32_e32 v3, v187, v3
	v_cvt_f16_f32_e32 v3, v3
	v_add_f32_e32 v4, v187, v4
	v_cvt_f16_f32_e32 v4, v4
	v_add_f32_e32 v5, v187, v5
	v_cvt_f16_f32_e32 v5, v5
	v_add_f32_e32 v6, v187, v6
	v_cvt_f16_f32_e32 v6, v6
	v_add_f32_e32 v7, v187, v7
	v_cvt_f16_f32_e32 v7, v7
	v_add_f32_e32 v8, v187, v8
	v_cvt_f16_f32_e32 v8, v8
	v_add_f32_e32 v9, v187, v9
	v_cvt_f16_f32_e32 v9, v9
	v_add_f32_e32 v10, v187, v10
	v_cvt_f16_f32_e32 v10, v10
	v_add_f32_e32 v11, v187, v11
	v_cvt_f16_f32_e32 v11, v11
	v_add_f32_e32 v12, v187, v12
	v_cvt_f16_f32_e32 v12, v12
	v_add_f32_e32 v13, v187, v13
	v_cvt_f16_f32_e32 v13, v13
	v_add_f32_e32 v14, v187, v14
	v_cvt_f16_f32_e32 v14, v14
	v_add_f32_e32 v15, v187, v15
	v_cvt_f16_f32_e32 v15, v15
	v_add_f32_e32 v16, v187, v16
	v_cvt_f16_f32_e32 v16, v16
	v_add_f32_e32 v17, v187, v17
	v_cvt_f16_f32_e32 v17, v17
	s_add_u32 s2, s18, 0x0
	s_addc_u32 s3, s19, 0
	global_store_short v132, v114, s[2:3] sc1
	global_store_short v132, v98, s[2:3] offset:64 sc1
	s_add_u32 s2, s18, 0x3a00
	s_addc_u32 s3, s19, 0
	global_store_short v132, v115, s[2:3] sc1
	global_store_short v132, v99, s[2:3] offset:64 sc1
	s_add_u32 s2, s18, 0x7400
	s_addc_u32 s3, s19, 0
	global_store_short v132, v116, s[2:3] sc1
	global_store_short v132, v100, s[2:3] offset:64 sc1
	s_add_u32 s2, s18, 0xae00
	s_addc_u32 s3, s19, 0
	global_store_short v132, v117, s[2:3] sc1
	global_store_short v132, v101, s[2:3] offset:64 sc1
	s_add_u32 s2, s18, 0x1d000
	s_addc_u32 s3, s19, 0
	global_store_short v132, v118, s[2:3] sc1
	global_store_short v132, v102, s[2:3] offset:64 sc1
	s_add_u32 s2, s18, 0x20a00
	s_addc_u32 s3, s19, 0
	global_store_short v132, v119, s[2:3] sc1
	global_store_short v132, v103, s[2:3] offset:64 sc1
	s_add_u32 s2, s18, 0x24400
	s_addc_u32 s3, s19, 0
	global_store_short v132, v120, s[2:3] sc1
	global_store_short v132, v104, s[2:3] offset:64 sc1
	s_add_u32 s2, s18, 0x27e00
	s_addc_u32 s3, s19, 0
	global_store_short v132, v121, s[2:3] sc1
	global_store_short v132, v105, s[2:3] offset:64 sc1
	s_add_u32 s2, s18, 0x3a000
	s_addc_u32 s3, s19, 0
	global_store_short v132, v122, s[2:3] sc1
	global_store_short v132, v106, s[2:3] offset:64 sc1
	s_add_u32 s2, s18, 0x3da00
	s_addc_u32 s3, s19, 0
	global_store_short v132, v123, s[2:3] sc1
	global_store_short v132, v107, s[2:3] offset:64 sc1
	s_add_u32 s2, s18, 0x41400
	s_addc_u32 s3, s19, 0
	global_store_short v132, v124, s[2:3] sc1
	global_store_short v132, v108, s[2:3] offset:64 sc1
	s_add_u32 s2, s18, 0x44e00
	s_addc_u32 s3, s19, 0
	global_store_short v132, v125, s[2:3] sc1
	global_store_short v132, v109, s[2:3] offset:64 sc1
	s_add_u32 s2, s18, 0x57000
	s_addc_u32 s3, s19, 0
	global_store_short v132, v126, s[2:3] sc1
	global_store_short v132, v110, s[2:3] offset:64 sc1
	s_add_u32 s2, s18, 0x5aa00
	s_addc_u32 s3, s19, 0
	global_store_short v132, v127, s[2:3] sc1
	global_store_short v132, v111, s[2:3] offset:64 sc1
	s_add_u32 s2, s18, 0x5e400
	s_addc_u32 s3, s19, 0
	global_store_short v132, v128, s[2:3] sc1
	global_store_short v132, v112, s[2:3] offset:64 sc1
	s_add_u32 s2, s18, 0x61e00
	s_addc_u32 s3, s19, 0
	global_store_short v132, v129, s[2:3] sc1
	global_store_short v132, v113, s[2:3] offset:64 sc1
	s_add_u32 s2, s18, 0x74000
	s_addc_u32 s3, s19, 0
	global_store_short v132, v82, s[2:3] sc1
	global_store_short v132, v66, s[2:3] offset:64 sc1
	s_add_u32 s2, s18, 0x77a00
	s_addc_u32 s3, s19, 0
	global_store_short v132, v83, s[2:3] sc1
	global_store_short v132, v67, s[2:3] offset:64 sc1
	s_add_u32 s2, s18, 0x7b400
	s_addc_u32 s3, s19, 0
	global_store_short v132, v84, s[2:3] sc1
	global_store_short v132, v68, s[2:3] offset:64 sc1
	s_add_u32 s2, s18, 0x7ee00
	s_addc_u32 s3, s19, 0
	global_store_short v132, v85, s[2:3] sc1
	global_store_short v132, v69, s[2:3] offset:64 sc1
	s_add_u32 s2, s18, 0x91000
	s_addc_u32 s3, s19, 0
	global_store_short v132, v86, s[2:3] sc1
	global_store_short v132, v70, s[2:3] offset:64 sc1
	s_add_u32 s2, s18, 0x94a00
	s_addc_u32 s3, s19, 0
	global_store_short v132, v87, s[2:3] sc1
	global_store_short v132, v71, s[2:3] offset:64 sc1
	s_add_u32 s2, s18, 0x98400
	s_addc_u32 s3, s19, 0
	global_store_short v132, v88, s[2:3] sc1
	global_store_short v132, v72, s[2:3] offset:64 sc1
	s_add_u32 s2, s18, 0x9be00
	s_addc_u32 s3, s19, 0
	global_store_short v132, v89, s[2:3] sc1
	global_store_short v132, v73, s[2:3] offset:64 sc1
	s_add_u32 s2, s18, 0xae000
	s_addc_u32 s3, s19, 0
	global_store_short v132, v90, s[2:3] sc1
	global_store_short v132, v74, s[2:3] offset:64 sc1
	s_add_u32 s2, s18, 0xb1a00
	s_addc_u32 s3, s19, 0
	global_store_short v132, v91, s[2:3] sc1
	global_store_short v132, v75, s[2:3] offset:64 sc1
	s_add_u32 s2, s18, 0xb5400
	s_addc_u32 s3, s19, 0
	global_store_short v132, v92, s[2:3] sc1
	global_store_short v132, v76, s[2:3] offset:64 sc1
	s_add_u32 s2, s18, 0xb8e00
	s_addc_u32 s3, s19, 0
	global_store_short v132, v93, s[2:3] sc1
	global_store_short v132, v77, s[2:3] offset:64 sc1
	s_add_u32 s2, s18, 0xcb000
	s_addc_u32 s3, s19, 0
	global_store_short v132, v94, s[2:3] sc1
	global_store_short v132, v78, s[2:3] offset:64 sc1
	s_add_u32 s2, s18, 0xcea00
	s_addc_u32 s3, s19, 0
	global_store_short v132, v95, s[2:3] sc1
	global_store_short v132, v79, s[2:3] offset:64 sc1
	s_add_u32 s2, s18, 0xd2400
	s_addc_u32 s3, s19, 0
	global_store_short v132, v96, s[2:3] sc1
;   __device__ __forceinline__ half_t* u() const { return (half_t*)(ws() + OFF_u); }
; __device__ __forceinline__ void phase_inproj(const KP& p, int l, char* smem, int* q, int xcc) {
;     ...
;           p.u()[(size_t)tok * NU + n0 + col] = hv;
;           if (vT) {
	global_store_short v132, v80, s[2:3] offset:64 sc1
	s_add_u32 s2, s18, 0xd5e00
	s_addc_u32 s3, s19, 0
	global_store_short v132, v97, s[2:3] sc1
	global_store_short v132, v81, s[2:3] offset:64 sc1
	s_add_u32 s2, s18, 0xe8000
	s_addc_u32 s3, s19, 0
	global_store_short v132, v50, s[2:3] sc1
	global_store_short v132, v34, s[2:3] offset:64 sc1
	s_add_u32 s2, s18, 0xeba00
	s_addc_u32 s3, s19, 0
	global_store_short v132, v51, s[2:3] sc1
	global_store_short v132, v35, s[2:3] offset:64 sc1
	s_add_u32 s2, s18, 0xef400
	s_addc_u32 s3, s19, 0
	global_store_short v132, v52, s[2:3] sc1
	global_store_short v132, v36, s[2:3] offset:64 sc1
	s_add_u32 s2, s18, 0xf2e00
	s_addc_u32 s3, s19, 0
	global_store_short v132, v53, s[2:3] sc1
	global_store_short v132, v37, s[2:3] offset:64 sc1
	s_add_u32 s2, s18, 0x105000
	s_addc_u32 s3, s19, 0
	global_store_short v132, v54, s[2:3] sc1
	global_store_short v132, v38, s[2:3] offset:64 sc1
	s_add_u32 s2, s18, 0x108a00
	s_addc_u32 s3, s19, 0
	global_store_short v132, v55, s[2:3] sc1
	global_store_short v132, v39, s[2:3] offset:64 sc1
	s_add_u32 s2, s18, 0x10c400
	s_addc_u32 s3, s19, 0
	global_store_short v132, v56, s[2:3] sc1
	global_store_short v132, v40, s[2:3] offset:64 sc1
	s_add_u32 s2, s18, 0x10fe00
	s_addc_u32 s3, s19, 0
	global_store_short v132, v57, s[2:3] sc1
	global_store_short v132, v41, s[2:3] offset:64 sc1
	s_add_u32 s2, s18, 0x122000
	s_addc_u32 s3, s19, 0
	global_store_short v132, v58, s[2:3] sc1
	global_store_short v132, v42, s[2:3] offset:64 sc1
	s_add_u32 s2, s18, 0x125a00
	s_addc_u32 s3, s19, 0
	global_store_short v132, v59, s[2:3] sc1
	global_store_short v132, v43, s[2:3] offset:64 sc1
	s_add_u32 s2, s18, 0x129400
	s_addc_u32 s3, s19, 0
	global_store_short v132, v60, s[2:3] sc1
	global_store_short v132, v44, s[2:3] offset:64 sc1
	s_add_u32 s2, s18, 0x12ce00
	s_addc_u32 s3, s19, 0
	global_store_short v132, v61, s[2:3] sc1
	global_store_short v132, v45, s[2:3] offset:64 sc1
	s_add_u32 s2, s18, 0x13f000
	s_addc_u32 s3, s19, 0
	global_store_short v132, v62, s[2:3] sc1
	global_store_short v132, v46, s[2:3] offset:64 sc1
	s_add_u32 s2, s18, 0x142a00
	s_addc_u32 s3, s19, 0
	global_store_short v132, v63, s[2:3] sc1
	global_store_short v132, v47, s[2:3] offset:64 sc1
	s_add_u32 s2, s18, 0x146400
	s_addc_u32 s3, s19, 0
	global_store_short v132, v64, s[2:3] sc1
	global_store_short v132, v48, s[2:3] offset:64 sc1
	s_add_u32 s2, s18, 0x149e00
	s_addc_u32 s3, s19, 0
	global_store_short v132, v65, s[2:3] sc1
	global_store_short v132, v49, s[2:3] offset:64 sc1
	s_add_u32 s2, s18, 0x15c000
	s_addc_u32 s3, s19, 0
	global_store_short v132, v18, s[2:3] sc1
	global_store_short v132, v2, s[2:3] offset:64 sc1
	s_add_u32 s2, s18, 0x15fa00
	s_addc_u32 s3, s19, 0
	global_store_short v132, v19, s[2:3] sc1
	global_store_short v132, v3, s[2:3] offset:64 sc1
	s_add_u32 s2, s18, 0x163400
	s_addc_u32 s3, s19, 0
	global_store_short v132, v20, s[2:3] sc1
	global_store_short v132, v4, s[2:3] offset:64 sc1
	s_add_u32 s2, s18, 0x166e00
	s_addc_u32 s3, s19, 0
	global_store_short v132, v21, s[2:3] sc1
	global_store_short v132, v5, s[2:3] offset:64 sc1
	s_add_u32 s2, s18, 0x179000
	s_addc_u32 s3, s19, 0
	global_store_short v132, v22, s[2:3] sc1
	global_store_short v132, v6, s[2:3] offset:64 sc1
	s_add_u32 s2, s18, 0x17ca00
	s_addc_u32 s3, s19, 0
	global_store_short v132, v23, s[2:3] sc1
	global_store_short v132, v7, s[2:3] offset:64 sc1
	s_add_u32 s2, s18, 0x180400
	s_addc_u32 s3, s19, 0
	global_store_short v132, v24, s[2:3] sc1
	global_store_short v132, v8, s[2:3] offset:64 sc1
	s_add_u32 s2, s18, 0x183e00
	s_addc_u32 s3, s19, 0
	global_store_short v132, v25, s[2:3] sc1
	global_store_short v132, v9, s[2:3] offset:64 sc1
	s_add_u32 s2, s18, 0x196000
	s_addc_u32 s3, s19, 0
	global_store_short v132, v26, s[2:3] sc1
	global_store_short v132, v10, s[2:3] offset:64 sc1
	s_add_u32 s2, s18, 0x199a00
	s_addc_u32 s3, s19, 0
	global_store_short v132, v27, s[2:3] sc1
	global_store_short v132, v11, s[2:3] offset:64 sc1
	s_add_u32 s2, s18, 0x19d400
	s_addc_u32 s3, s19, 0
	global_store_short v132, v28, s[2:3] sc1
	global_store_short v132, v12, s[2:3] offset:64 sc1
	s_add_u32 s2, s18, 0x1a0e00
	s_addc_u32 s3, s19, 0
	global_store_short v132, v29, s[2:3] sc1
	global_store_short v132, v13, s[2:3] offset:64 sc1
	s_add_u32 s2, s18, 0x1b3000
	s_addc_u32 s3, s19, 0
	global_store_short v132, v30, s[2:3] sc1
	global_store_short v132, v14, s[2:3] offset:64 sc1
	s_add_u32 s2, s18, 0x1b6a00
	s_addc_u32 s3, s19, 0
	global_store_short v132, v31, s[2:3] sc1
	global_store_short v132, v15, s[2:3] offset:64 sc1
	s_add_u32 s2, s18, 0x1ba400
	s_addc_u32 s3, s19, 0
	global_store_short v132, v32, s[2:3] sc1
	global_store_short v132, v16, s[2:3] offset:64 sc1
	s_add_u32 s2, s18, 0x1bde00
	s_addc_u32 s3, s19, 0
	global_store_short v132, v33, s[2:3] sc1
	global_store_short v132, v17, s[2:3] offset:64 sc1
	s_cmp_lg_u64 s[40:41], 0
	s_cbranch_scc0 .Lip_novt
; __device__ __forceinline__ void phase_inproj(const KP& p, int l, char* smem, int* q, int xcc) {
;     ...
;           if (vT) {
;             const int b = tok >> 13, t = tok & 8191;
;             vT[((size_t)(b * 2 + (col >> 6)) * 64 + (col & 63)) * SEQ + t] = hv;
;           }
	s_lshr_b32 s2, s14, 13
	s_lshl_b32 s2, s2, 21
	s_and_b32 s3, s14, 0x1fff
	s_lshl_b32 s3, s3, 1
	s_add_u32 s2, s2, s3
	s_add_u32 s40, s40, s2
	s_addc_u32 s41, s41, 0
	v_lshlrev_b32_e32 v135, 14, v134
	v_lshl_add_u32 v135, v130, 3, v135
	v_pack_b32_f16 v136, v114, v115
	v_pack_b32_f16 v137, v116, v117
	s_add_u32 s2, s40, 0x0
	s_addc_u32 s3, s41, 0
	global_store_dwordx2 v135, v[136:137], s[2:3]
	v_pack_b32_f16 v138, v118, v119
	v_pack_b32_f16 v139, v120, v121
	s_add_u32 s2, s40, 0x10
	s_addc_u32 s3, s41, 0
	global_store_dwordx2 v135, v[138:139], s[2:3]
	v_pack_b32_f16 v140, v122, v123
	v_pack_b32_f16 v141, v124, v125
	s_add_u32 s2, s40, 0x20
	s_addc_u32 s3, s41, 0
	global_store_dwordx2 v135, v[140:141], s[2:3]
	v_pack_b32_f16 v142, v126, v127
	v_pack_b32_f16 v143, v128, v129
	s_add_u32 s2, s40, 0x30
	s_addc_u32 s3, s41, 0
	global_store_dwordx2 v135, v[142:143], s[2:3]
	v_pack_b32_f16 v136, v98, v99
	v_pack_b32_f16 v137, v100, v101
	s_add_u32 s2, s40, 0x80000
	s_addc_u32 s3, s41, 0
	global_store_dwordx2 v135, v[136:137], s[2:3]
	v_pack_b32_f16 v138, v102, v103
	v_pack_b32_f16 v139, v104, v105
	s_add_u32 s2, s40, 0x80010
	s_addc_u32 s3, s41, 0
	global_store_dwordx2 v135, v[138:139], s[2:3]
	v_pack_b32_f16 v140, v106, v107
	v_pack_b32_f16 v141, v108, v109
	s_add_u32 s2, s40, 0x80020
	s_addc_u32 s3, s41, 0
	global_store_dwordx2 v135, v[140:141], s[2:3]
	v_pack_b32_f16 v142, v110, v111
	v_pack_b32_f16 v143, v112, v113
	s_add_u32 s2, s40, 0x80030
	s_addc_u32 s3, s41, 0
	global_store_dwordx2 v135, v[142:143], s[2:3]
	v_pack_b32_f16 v136, v82, v83
	v_pack_b32_f16 v137, v84, v85
	s_add_u32 s2, s40, 0x40
	s_addc_u32 s3, s41, 0
	global_store_dwordx2 v135, v[136:137], s[2:3]
	v_pack_b32_f16 v138, v86, v87
	v_pack_b32_f16 v139, v88, v89
	s_add_u32 s2, s40, 0x50
	s_addc_u32 s3, s41, 0
	global_store_dwordx2 v135, v[138:139], s[2:3]
	v_pack_b32_f16 v140, v90, v91
	v_pack_b32_f16 v141, v92, v93
	s_add_u32 s2, s40, 0x60
	s_addc_u32 s3, s41, 0
	global_store_dwordx2 v135, v[140:141], s[2:3]
	v_pack_b32_f16 v142, v94, v95
	v_pack_b32_f16 v143, v96, v97
	s_add_u32 s2, s40, 0x70
	s_addc_u32 s3, s41, 0
	global_store_dwordx2 v135, v[142:143], s[2:3]
	v_pack_b32_f16 v136, v66, v67
	v_pack_b32_f16 v137, v68, v69
	s_add_u32 s2, s40, 0x80040
	s_addc_u32 s3, s41, 0
	global_store_dwordx2 v135, v[136:137], s[2:3]
	v_pack_b32_f16 v138, v70, v71
	v_pack_b32_f16 v139, v72, v73
	s_add_u32 s2, s40, 0x80050
	s_addc_u32 s3, s41, 0
	global_store_dwordx2 v135, v[138:139], s[2:3]
	v_pack_b32_f16 v140, v74, v75
	v_pack_b32_f16 v141, v76, v77
	s_add_u32 s2, s40, 0x80060
	s_addc_u32 s3, s41, 0
	global_store_dwordx2 v135, v[140:141], s[2:3]
	v_pack_b32_f16 v142, v78, v79
	v_pack_b32_f16 v143, v80, v81
	s_add_u32 s2, s40, 0x80070
	s_addc_u32 s3, s41, 0
	global_store_dwordx2 v135, v[142:143], s[2:3]
	v_pack_b32_f16 v136, v50, v51
	v_pack_b32_f16 v137, v52, v53
	s_add_u32 s2, s40, 0x80
	s_addc_u32 s3, s41, 0
	global_store_dwordx2 v135, v[136:137], s[2:3]
	v_pack_b32_f16 v138, v54, v55
	v_pack_b32_f16 v139, v56, v57
	s_add_u32 s2, s40, 0x90
	s_addc_u32 s3, s41, 0
	global_store_dwordx2 v135, v[138:139], s[2:3]
	v_pack_b32_f16 v140, v58, v59
	v_pack_b32_f16 v141, v60, v61
	s_add_u32 s2, s40, 0xa0
	s_addc_u32 s3, s41, 0
	global_store_dwordx2 v135, v[140:141], s[2:3]
	v_pack_b32_f16 v142, v62, v63
	v_pack_b32_f16 v143, v64, v65
	s_add_u32 s2, s40, 0xb0
	s_addc_u32 s3, s41, 0
	global_store_dwordx2 v135, v[142:143], s[2:3]
	v_pack_b32_f16 v136, v34, v35
	v_pack_b32_f16 v137, v36, v37
	s_add_u32 s2, s40, 0x80080
	s_addc_u32 s3, s41, 0
	global_store_dwordx2 v135, v[136:137], s[2:3]
	v_pack_b32_f16 v138, v38, v39
	v_pack_b32_f16 v139, v40, v41
	s_add_u32 s2, s40, 0x80090
	s_addc_u32 s3, s41, 0
	global_store_dwordx2 v135, v[138:139], s[2:3]
	v_pack_b32_f16 v140, v42, v43
	v_pack_b32_f16 v141, v44, v45
	s_add_u32 s2, s40, 0x800a0
	s_addc_u32 s3, s41, 0
	global_store_dwordx2 v135, v[140:141], s[2:3]
	v_pack_b32_f16 v142, v46, v47
	v_pack_b32_f16 v143, v48, v49
	s_add_u32 s2, s40, 0x800b0
	s_addc_u32 s3, s41, 0
	global_store_dwordx2 v135, v[142:143], s[2:3]
	v_pack_b32_f16 v136, v18, v19
	v_pack_b32_f16 v137, v20, v21
	s_add_u32 s2, s40, 0xc0
	s_addc_u32 s3, s41, 0
	global_store_dwordx2 v135, v[136:137], s[2:3]
	v_pack_b32_f16 v138, v22, v23
	v_pack_b32_f16 v139, v24, v25
	s_add_u32 s2, s40, 0xd0
	s_addc_u32 s3, s41, 0
	global_store_dwordx2 v135, v[138:139], s[2:3]
	v_pack_b32_f16 v140, v26, v27
	v_pack_b32_f16 v141, v28, v29
	s_add_u32 s2, s40, 0xe0
	s_addc_u32 s3, s41, 0
	global_store_dwordx2 v135, v[140:141], s[2:3]
	v_pack_b32_f16 v142, v30, v31
	v_pack_b32_f16 v143, v32, v33
	s_add_u32 s2, s40, 0xf0
	s_addc_u32 s3, s41, 0
	global_store_dwordx2 v135, v[142:143], s[2:3]
	v_pack_b32_f16 v136, v2, v3
	v_pack_b32_f16 v137, v4, v5
	s_add_u32 s2, s40, 0x800c0
	s_addc_u32 s3, s41, 0
	global_store_dwordx2 v135, v[136:137], s[2:3]
	v_pack_b32_f16 v138, v6, v7
	v_pack_b32_f16 v139, v8, v9
	s_add_u32 s2, s40, 0x800d0
	s_addc_u32 s3, s41, 0
	global_store_dwordx2 v135, v[138:139], s[2:3]
	v_pack_b32_f16 v140, v10, v11
	v_pack_b32_f16 v141, v12, v13
	s_add_u32 s2, s40, 0x800e0
	s_addc_u32 s3, s41, 0
	global_store_dwordx2 v135, v[140:141], s[2:3]
	v_pack_b32_f16 v142, v14, v15
	v_pack_b32_f16 v143, v16, v17
	s_add_u32 s2, s40, 0x800f0
	s_addc_u32 s3, s41, 0
	global_store_dwordx2 v135, v[142:143], s[2:3]
